# P2b: odd workgroups run their prep tile before the q/k norm pass (overlap ALU-bound and bandwidth-bound halves)
# baseline (speedup 1.0000x reference)
; __global__ void __launch_bounds__(NTHR, 2) hybrid_fwd(Args args) {
;     ...
;     {   for (int g = blockIdx.x; g < T / 64; g += F.G) p2b_fgroup(F, args, g);
;         for (int m = F.gw; m < M; m += F.NGW) p2_qknorm_row(args, m, F.lane);
;         for (int tile = blockIdx.x; tile < T / 32; tile += F.G) p2_rwprep_tile(F, args, tile * 32); }
.LBB0_317:
	s_cmp_lg_u32 s99, 0
	s_cbranch_scc1 .Lswap_norm
	s_bitcmp1_b32 s94, 0
	s_cbranch_scc0 .Lswap_norm
	s_mov_b32 s99, 1
	v_writelane_b32 v255, s10, 24
	v_writelane_b32 v255, s11, 25
	v_lshlrev_b32_e32 v0, 4, v10
	s_branch .LBB0_320

; __global__ void __launch_bounds__(NTHR, 2) hybrid_fwd(Args args) {
;     ...
;         for (int m = F.gw; m < M; m += F.NGW) p2_qknorm_row(args, m, F.lane);
;         for (int tile = blockIdx.x; tile < T / 32; tile += F.G) p2_rwprep_tile(F, args, tile * 32); }
.LBB0_320:
	s_cmp_eq_u32 s99, 2
	s_cbranch_scc1 .LBB0_347
	s_cmpk_lt_i32 s94, 0x200
	s_cselect_b64 s[0:1], -1, 0
	v_writelane_b32 v254, s0, 41
	s_cmpk_gt_i32 s94, 0x1ff
	s_nop 0
	v_writelane_b32 v254, s1, 42
	s_cbranch_scc1 .LBB0_347
	v_writelane_b32 v255, s36, 8
	v_writelane_b32 v255, s37, 9
	v_writelane_b32 v255, s38, 10
	v_writelane_b32 v255, s39, 11
	v_writelane_b32 v255, s40, 12
	v_writelane_b32 v255, s41, 13
	v_writelane_b32 v255, s42, 14
	v_writelane_b32 v255, s43, 15
	v_writelane_b32 v255, s44, 16
	v_writelane_b32 v255, s45, 17
	v_writelane_b32 v255, s46, 18
	v_writelane_b32 v255, s47, 19
	v_writelane_b32 v255, s48, 20
	v_writelane_b32 v255, s49, 21
	v_writelane_b32 v255, s50, 22
	v_writelane_b32 v255, s51, 23

; __global__ void __launch_bounds__(NTHR, 2) hybrid_fwd(Args args) {
;     ...
;     {   for (int g = blockIdx.x; g < T / 64; g += F.G) p2b_fgroup(F, args, g);
;         for (int m = F.gw; m < M; m += F.NGW) p2_qknorm_row(args, m, F.lane);
;         for (int tile = blockIdx.x; tile < T / 32; tile += F.G) p2_rwprep_tile(F, args, tile * 32); }
.LBB0_347:
	s_cmp_eq_u32 s98, 1
	s_cbranch_scc1 .Lrw_late_done
	s_cmp_lg_u32 s99, 1
	s_cbranch_scc1 .Lswap_done
	s_mov_b32 s99, 2
	v_readlane_b32 s10, v255, 24
	v_readlane_b32 s11, v255, 25
	v_mbcnt_lo_u32_b32 v10, -1, 0
	v_mbcnt_hi_u32_b32 v10, -1, v10
	s_nop 4
	s_branch .LBB0_317
